# phase-3 triangular-solve block: 30 redundant address copies (v3 = v2 + 0) removed, LDS reads address v2 directly; last 8 bf16 bit-trick conversions -> v_cvt_pk_bf16_f32
# baseline (speedup 1.0000x reference)
.LBB0_355:
	s_and_b64 vcc, exec, s[18:19]
	s_cbranch_vccz .LBB0_421
	v_add_u32_e32 v2, v171, v187
	ds_read_b128 v[4:7], v2 offset:272
	v_mov_b32_e32 v2, v188
	s_waitcnt lgkmcnt(0)
	v_fma_f32 v17, -v195, v4, v196
	ds_read_b128 v[6:9], v2 offset:544
	s_nop 0
	s_waitcnt lgkmcnt(0)
	ds_read_b128 v[8:11], v2 offset:816
	v_fma_f32 v3, -v195, v6, v197
	v_fma_f32 v4, -v7, v17, 0
	v_add_f32_e32 v15, v4, v3
	s_nop 0
	ds_read_b128 v[4:7], v2 offset:1088
	s_waitcnt lgkmcnt(1)
	v_fma_f32 v3, -v195, v8, v198
	v_fma_f32 v8, -v17, v9, 0
	v_fma_f32 v9, -v10, v15, 0
	v_add_f32_e32 v3, v8, v3
	v_add_f32_e32 v13, v9, v3
	s_nop 0
	ds_read_b128 v[18:21], v2 offset:1360
	ds_read_b128 v[8:11], v2 offset:1376
	s_waitcnt lgkmcnt(2)
	v_fma_f32 v3, -v195, v4, v199
	v_fma_f32 v4, -v17, v5, 0
	v_fma_f32 v5, -v15, v6, 0
	v_fma_f32 v6, -v7, v13, 0
	v_add_f32_e32 v3, v4, v3
	v_add_f32_e32 v4, v6, v5
	s_waitcnt lgkmcnt(0)
	v_add_f32_e32 v11, v4, v3
	v_fma_f32 v9, -v17, v19, 0
	ds_read_b128 v[4:7], v2 offset:1632
	ds_read_b128 v[22:25], v2 offset:1648
	v_fma_f32 v3, -v195, v18, v200
	v_fma_f32 v10, -v15, v20, 0
	v_fma_f32 v12, -v13, v21, 0
	v_fma_f32 v3, -v8, v11, v3
	v_add_f32_e32 v3, v9, v3
	v_add_f32_e32 v8, v12, v10
	v_add_f32_e32 v9, v8, v3
	s_nop 0
	ds_read_b128 v[18:21], v2 offset:1904
	ds_read_b128 v[28:31], v2 offset:1920
	s_waitcnt lgkmcnt(3)
	v_fma_f32 v3, -v195, v4, v201
	v_fma_f32 v4, -v17, v5, 0
	v_fma_f32 v5, -v15, v6, 0
	v_fma_f32 v6, -v13, v7, 0
	s_waitcnt lgkmcnt(2)
	v_fma_f32 v3, -v11, v22, v3
	v_fma_f32 v4, -v23, v9, v4
	v_add_f32_e32 v3, v4, v3
	v_add_f32_e32 v4, v6, v5
	v_add_f32_e32 v7, v4, v3
	s_waitcnt lgkmcnt(1)
	v_fma_f32 v4, -v17, v19, 0
	ds_read_b128 v[22:25], v2 offset:2176
	ds_read_b128 v[32:35], v2 offset:2192
	v_fma_f32 v3, -v195, v18, v202
	v_fma_f32 v5, -v15, v20, 0
	v_fma_f32 v6, -v13, v21, 0
	s_waitcnt lgkmcnt(2)
	v_fma_f32 v3, -v11, v28, v3
	v_fma_f32 v4, -v9, v29, v4
	v_fma_f32 v5, -v30, v7, v5
	v_add_f32_e32 v3, v4, v3
	v_add_f32_e32 v4, v6, v5
	v_add_f32_e32 v4, v4, v3
	s_waitcnt lgkmcnt(1)
	v_fma_f32 v5, -v17, v23, 0
	ds_read_b128 v[18:21], v2 offset:2448
	ds_read_b128 v[28:31], v2 offset:2464
	ds_read_b128 v[36:39], v2 offset:2480
	v_fma_f32 v3, -v195, v22, v203
	v_fma_f32 v6, -v15, v24, 0
	v_fma_f32 v8, -v13, v25, 0
	s_waitcnt lgkmcnt(3)
	v_fma_f32 v3, -v11, v32, v3
	v_fma_f32 v5, -v9, v33, v5
	v_fma_f32 v6, -v7, v34, v6
	v_fma_f32 v8, -v35, v4, v8
	v_add_f32_e32 v3, v5, v3
	v_add_f32_e32 v5, v8, v6
	v_add_f32_e32 v5, v5, v3
	s_waitcnt lgkmcnt(2)
	v_fma_f32 v6, -v17, v19, 0
	ds_read_b128 v[22:25], v2 offset:2720
	ds_read_b128 v[32:35], v2 offset:2736
	s_waitcnt lgkmcnt(2)
	ds_read_b128 v[38:41], v2 offset:2752
	v_fma_f32 v3, -v195, v18, v204
	v_fma_f32 v8, -v15, v20, 0
	v_fma_f32 v10, -v13, v21, 0
	v_fma_f32 v3, -v11, v28, v3
	v_fma_f32 v6, -v9, v29, v6
	v_fma_f32 v8, -v7, v30, v8
	v_fma_f32 v10, -v4, v31, v10
	v_fma_f32 v3, -v36, v5, v3
	v_add_f32_e32 v3, v6, v3
	v_add_f32_e32 v6, v10, v8
	v_add_f32_e32 v6, v6, v3
	s_waitcnt lgkmcnt(2)
	v_fma_f32 v8, -v17, v23, 0
	ds_read_b128 v[18:21], v2 offset:2992
	ds_read_b128 v[28:31], v2 offset:3008
	s_waitcnt lgkmcnt(2)
	ds_read_b128 v[40:43], v2 offset:3024
	v_fma_f32 v3, -v195, v22, v205
	v_fma_f32 v10, -v15, v24, 0
	v_fma_f32 v12, -v13, v25, 0
	v_fma_f32 v3, -v11, v32, v3
	v_fma_f32 v8, -v9, v33, v8
	v_fma_f32 v10, -v7, v34, v10
	v_fma_f32 v12, -v4, v35, v12
	v_fma_f32 v3, -v5, v38, v3
	v_fma_f32 v8, -v39, v6, v8
	v_add_f32_e32 v3, v8, v3
	v_add_f32_e32 v8, v12, v10
	v_add_f32_e32 v8, v8, v3
	s_waitcnt lgkmcnt(2)
	v_fma_f32 v10, -v17, v19, 0
	ds_read_b128 v[22:25], v2 offset:3264
	ds_read_b128 v[32:35], v2 offset:3280
	ds_read_b128 v[36:39], v2 offset:3296
	v_fma_f32 v3, -v195, v18, v206
	v_fma_f32 v12, -v15, v20, 0
	v_fma_f32 v14, -v13, v21, 0
	s_waitcnt lgkmcnt(4)
	v_fma_f32 v3, -v11, v28, v3
	v_fma_f32 v10, -v9, v29, v10
	v_fma_f32 v12, -v7, v30, v12
	v_fma_f32 v14, -v4, v31, v14
	s_waitcnt lgkmcnt(3)
	v_fma_f32 v3, -v5, v40, v3
	v_fma_f32 v10, -v6, v41, v10
	v_fma_f32 v12, -v42, v8, v12
	v_add_f32_e32 v3, v10, v3
	v_add_f32_e32 v10, v14, v12
	v_add_f32_e32 v10, v10, v3
	s_waitcnt lgkmcnt(2)
	v_fma_f32 v12, -v17, v23, 0
	ds_read_b128 v[18:21], v2 offset:3536
	ds_read_b128 v[28:31], v2 offset:3552
	ds_read_b128 v[40:43], v2 offset:3568
	ds_read_b128 v[44:47], v2 offset:3584
	v_fma_f32 v3, -v195, v22, v207
	v_fma_f32 v14, -v15, v24, 0
	v_fma_f32 v16, -v13, v25, 0
	s_waitcnt lgkmcnt(5)
	v_fma_f32 v3, -v11, v32, v3
	v_fma_f32 v12, -v9, v33, v12
	v_fma_f32 v14, -v7, v34, v14
	v_fma_f32 v16, -v4, v35, v16
	s_waitcnt lgkmcnt(4)
	v_fma_f32 v3, -v5, v36, v3
	v_fma_f32 v12, -v6, v37, v12
	v_fma_f32 v14, -v8, v38, v14
	v_fma_f32 v16, -v39, v10, v16
	v_add_f32_e32 v3, v12, v3
	v_add_f32_e32 v12, v16, v14
	v_add_f32_e32 v12, v12, v3
	s_waitcnt lgkmcnt(3)
	v_fma_f32 v14, -v17, v19, 0
	ds_read_b128 v[22:25], v2 offset:3808
	ds_read_b128 v[32:35], v2 offset:3824
	ds_read_b128 v[36:39], v2 offset:3840
	s_waitcnt lgkmcnt(3)
	ds_read_b128 v[46:49], v2 offset:3856
	v_fma_f32 v3, -v195, v18, v208
	v_fma_f32 v16, -v15, v20, 0
	v_fma_f32 v18, -v13, v21, 0
	v_fma_f32 v3, -v11, v28, v3
	v_fma_f32 v14, -v9, v29, v14
	v_fma_f32 v16, -v7, v30, v16
	v_fma_f32 v18, -v4, v31, v18
	v_fma_f32 v3, -v5, v40, v3
	v_fma_f32 v14, -v6, v41, v14
	v_fma_f32 v16, -v8, v42, v16
	v_fma_f32 v18, -v10, v43, v18
	v_fma_f32 v3, -v44, v12, v3
	v_add_f32_e32 v3, v14, v3
	v_add_f32_e32 v14, v18, v16
	v_add_f32_e32 v14, v14, v3
	s_waitcnt lgkmcnt(3)
	v_fma_f32 v16, -v17, v23, 0
	ds_read_b128 v[18:21], v2 offset:4080
	ds_read_b128 v[28:31], v2 offset:4096
	ds_read_b128 v[40:43], v2 offset:4112
	s_waitcnt lgkmcnt(3)
	ds_read_b128 v[48:51], v2 offset:4128
	v_fma_f32 v3, -v195, v22, v209
	v_fma_f32 v22, -v15, v24, 0
	v_fma_f32 v23, -v13, v25, 0
	v_fma_f32 v3, -v11, v32, v3
	v_fma_f32 v16, -v9, v33, v16
	v_fma_f32 v22, -v7, v34, v22
	v_fma_f32 v23, -v4, v35, v23
	v_fma_f32 v3, -v5, v36, v3
	v_fma_f32 v16, -v6, v37, v16
	v_fma_f32 v22, -v8, v38, v22
	v_fma_f32 v23, -v10, v39, v23
	v_fma_f32 v3, -v12, v46, v3
	v_fma_f32 v16, -v47, v14, v16
	v_add_f32_e32 v3, v16, v3
	v_add_f32_e32 v16, v23, v22
	v_add_f32_e32 v16, v16, v3
	s_nop 0
	ds_read_b128 v[22:25], v2 offset:4352
	ds_read_b128 v[32:35], v2 offset:4368
	ds_read_b128 v[36:39], v2 offset:4384
	ds_read_b128 v[44:47], v2 offset:4400
	s_waitcnt lgkmcnt(7)
	v_fma_f32 v3, -v195, v18, v210
	v_fma_f32 v18, -v17, v19, 0
	v_fma_f32 v19, -v15, v20, 0
	v_fma_f32 v20, -v13, v21, 0
	s_waitcnt lgkmcnt(6)
	v_fma_f32 v3, -v11, v28, v3
	v_fma_f32 v18, -v9, v29, v18
	v_fma_f32 v19, -v7, v30, v19
	v_fma_f32 v20, -v4, v31, v20
	s_waitcnt lgkmcnt(5)
	v_fma_f32 v3, -v5, v40, v3
	v_fma_f32 v18, -v6, v41, v18
	v_fma_f32 v19, -v8, v42, v19
	v_fma_f32 v20, -v10, v43, v20
	s_waitcnt lgkmcnt(4)
	v_fma_f32 v3, -v12, v48, v3
	v_fma_f32 v18, -v14, v49, v18
	v_fma_f32 v19, -v50, v16, v19
	v_add_f32_e32 v3, v18, v3
	v_add_f32_e32 v18, v20, v19
	v_add_f32_e32 v18, v18, v3
	s_waitcnt lgkmcnt(3)
	v_fma_f32 v19, -v17, v23, 0
	ds_read_b128 v[28:31], v2 offset:4624
	ds_read_b128 v[40:43], v2 offset:4640
	ds_read_b128 v[48:51], v2 offset:4656
	ds_read_b128 v[52:55], v2 offset:4672
	ds_read_b128 v[56:59], v2 offset:4688
	v_fma_f32 v3, -v195, v22, v211
	v_fma_f32 v20, -v15, v24, 0
	v_fma_f32 v21, -v13, v25, 0
	s_waitcnt lgkmcnt(7)
	v_fma_f32 v3, -v11, v32, v3
	v_fma_f32 v19, -v9, v33, v19
	v_fma_f32 v20, -v7, v34, v20
	v_fma_f32 v21, -v4, v35, v21
	s_waitcnt lgkmcnt(6)
	v_fma_f32 v3, -v5, v36, v3
	v_fma_f32 v19, -v6, v37, v19
	v_fma_f32 v20, -v8, v38, v20
	v_fma_f32 v21, -v10, v39, v21
	s_waitcnt lgkmcnt(5)
	v_fma_f32 v3, -v12, v44, v3
	v_fma_f32 v19, -v14, v45, v19
	v_fma_f32 v20, -v16, v46, v20
	v_fma_f32 v21, -v47, v18, v21
	v_add_f32_e32 v3, v19, v3
	v_add_f32_e32 v19, v21, v20
	v_add_f32_e32 v19, v19, v3
	s_waitcnt lgkmcnt(4)
	v_fma_f32 v20, -v17, v29, 0
	ds_read_b128 v[22:25], v2 offset:4896
	ds_read_b128 v[32:35], v2 offset:4912
	ds_read_b128 v[36:39], v2 offset:4928
	ds_read_b128 v[44:47], v2 offset:4944
	s_waitcnt lgkmcnt(4)
	ds_read_b128 v[58:61], v2 offset:4960
	v_fma_f32 v3, -v195, v28, v212
	v_fma_f32 v21, -v15, v30, 0
	v_fma_f32 v27, -v13, v31, 0
	v_fma_f32 v3, -v11, v40, v3
	v_fma_f32 v20, -v9, v41, v20
	v_fma_f32 v21, -v7, v42, v21
	v_fma_f32 v27, -v4, v43, v27
	v_fma_f32 v3, -v5, v48, v3
	v_fma_f32 v20, -v6, v49, v20
	v_fma_f32 v21, -v8, v50, v21
	v_fma_f32 v27, -v10, v51, v27
	v_fma_f32 v3, -v12, v52, v3
	v_fma_f32 v20, -v14, v53, v20
	v_fma_f32 v21, -v16, v54, v21
	v_fma_f32 v27, -v18, v55, v27
	v_fma_f32 v3, -v56, v19, v3
	v_add_f32_e32 v3, v20, v3
	v_add_f32_e32 v20, v27, v21
	v_add_f32_e32 v20, v20, v3
	s_waitcnt lgkmcnt(4)
	v_fma_f32 v21, -v17, v23, 0
	ds_read_b128 v[28:31], v2 offset:5168
	ds_read_b128 v[40:43], v2 offset:5184
	ds_read_b128 v[48:51], v2 offset:5200
	ds_read_b128 v[52:55], v2 offset:5216
	s_waitcnt lgkmcnt(4)
	ds_read_b128 v[60:63], v2 offset:5232
	v_fma_f32 v3, -v195, v22, v213
	v_fma_f32 v22, -v15, v24, 0
	v_fma_f32 v23, -v13, v25, 0
	v_fma_f32 v3, -v11, v32, v3
	v_fma_f32 v21, -v9, v33, v21
	v_fma_f32 v22, -v7, v34, v22
	v_fma_f32 v23, -v4, v35, v23
	v_fma_f32 v3, -v5, v36, v3
	v_fma_f32 v21, -v6, v37, v21
	v_fma_f32 v22, -v8, v38, v22
	v_fma_f32 v23, -v10, v39, v23
	v_fma_f32 v3, -v12, v44, v3
	v_fma_f32 v21, -v14, v45, v21
	v_fma_f32 v22, -v16, v46, v22
	v_fma_f32 v23, -v18, v47, v23
	v_fma_f32 v3, -v19, v58, v3
	v_fma_f32 v21, -v59, v20, v21
	v_add_f32_e32 v3, v21, v3
	v_add_f32_e32 v21, v23, v22
	v_add_f32_e32 v21, v21, v3
	s_waitcnt lgkmcnt(4)
	v_fma_f32 v22, -v17, v29, 0
	ds_read_b128 v[32:35], v2 offset:5440
	ds_read_b128 v[36:39], v2 offset:5456
	ds_read_b128 v[44:47], v2 offset:5472
	ds_read_b128 v[56:59], v2 offset:5488
	ds_read_b128 v[64:67], v2 offset:5504
	v_fma_f32 v3, -v195, v28, v214
	v_fma_f32 v23, -v15, v30, 0
	v_fma_f32 v24, -v13, v31, 0
	s_waitcnt lgkmcnt(8)
	v_fma_f32 v3, -v11, v40, v3
	v_fma_f32 v22, -v9, v41, v22
	v_fma_f32 v23, -v7, v42, v23
	v_fma_f32 v24, -v4, v43, v24
	s_waitcnt lgkmcnt(7)
	v_fma_f32 v3, -v5, v48, v3
	v_fma_f32 v22, -v6, v49, v22
	v_fma_f32 v23, -v8, v50, v23
	v_fma_f32 v24, -v10, v51, v24
	s_waitcnt lgkmcnt(6)
	v_fma_f32 v3, -v12, v52, v3
	v_fma_f32 v22, -v14, v53, v22
	v_fma_f32 v23, -v16, v54, v23
	v_fma_f32 v24, -v18, v55, v24
	s_waitcnt lgkmcnt(5)
	v_fma_f32 v3, -v19, v60, v3
	v_fma_f32 v22, -v20, v61, v22
	v_fma_f32 v23, -v62, v21, v23
	v_add_f32_e32 v3, v22, v3
	v_add_f32_e32 v22, v24, v23
	v_add_f32_e32 v22, v22, v3
	s_waitcnt lgkmcnt(4)
	v_fma_f32 v23, -v17, v33, 0
	ds_read_b128 v[28:31], v2 offset:5712
	ds_read_b128 v[40:43], v2 offset:5728
	ds_read_b128 v[48:51], v2 offset:5744
	ds_read_b128 v[52:55], v2 offset:5760
	ds_read_b128 v[60:63], v2 offset:5776
	ds_read_b128 v[68:71], v2 offset:5792
	v_fma_f32 v3, -v195, v32, v215
	v_fma_f32 v24, -v15, v34, 0
	v_fma_f32 v25, -v13, v35, 0
	s_waitcnt lgkmcnt(9)
	v_fma_f32 v3, -v11, v36, v3
	v_fma_f32 v23, -v9, v37, v23
	v_fma_f32 v24, -v7, v38, v24
	v_fma_f32 v25, -v4, v39, v25
	s_waitcnt lgkmcnt(8)
	v_fma_f32 v3, -v5, v44, v3
	v_fma_f32 v23, -v6, v45, v23
	v_fma_f32 v24, -v8, v46, v24
	v_fma_f32 v25, -v10, v47, v25
	s_waitcnt lgkmcnt(7)
	v_fma_f32 v3, -v12, v56, v3
	v_fma_f32 v23, -v14, v57, v23
	v_fma_f32 v24, -v16, v58, v24
	v_fma_f32 v25, -v18, v59, v25
	s_waitcnt lgkmcnt(6)
	v_fma_f32 v3, -v19, v64, v3
	v_fma_f32 v23, -v20, v65, v23
	v_fma_f32 v24, -v21, v66, v24
	v_fma_f32 v25, -v67, v22, v25
	v_add_f32_e32 v3, v23, v3
	v_add_f32_e32 v23, v25, v24
	v_add_f32_e32 v23, v23, v3
	s_waitcnt lgkmcnt(5)
	v_fma_f32 v24, -v17, v29, 0
	ds_read_b128 v[32:35], v2 offset:5984
	ds_read_b128 v[36:39], v2 offset:6000
	ds_read_b128 v[44:47], v2 offset:6016
	ds_read_b128 v[56:59], v2 offset:6032
	ds_read_b128 v[64:67], v2 offset:6048
	s_waitcnt lgkmcnt(5)
	ds_read_b128 v[70:73], v2 offset:6064
	v_fma_f32 v3, -v195, v28, v216
	v_fma_f32 v25, -v15, v30, 0
	v_fma_f32 v27, -v13, v31, 0
	v_fma_f32 v3, -v11, v40, v3
	v_fma_f32 v24, -v9, v41, v24
	v_fma_f32 v25, -v7, v42, v25
	v_fma_f32 v27, -v4, v43, v27
	v_fma_f32 v3, -v5, v48, v3
	v_fma_f32 v24, -v6, v49, v24
	v_fma_f32 v25, -v8, v50, v25
	v_fma_f32 v27, -v10, v51, v27
	v_fma_f32 v3, -v12, v52, v3
	v_fma_f32 v24, -v14, v53, v24
	v_fma_f32 v25, -v16, v54, v25
	v_fma_f32 v27, -v18, v55, v27
	v_fma_f32 v3, -v19, v60, v3
	v_fma_f32 v24, -v20, v61, v24
	v_fma_f32 v25, -v21, v62, v25
	v_fma_f32 v27, -v22, v63, v27
	v_fma_f32 v3, -v68, v23, v3
	v_add_f32_e32 v3, v24, v3
	v_add_f32_e32 v24, v27, v25
	v_add_f32_e32 v24, v24, v3
	s_waitcnt lgkmcnt(5)
	v_fma_f32 v25, -v17, v33, 0
	ds_read_b128 v[28:31], v2 offset:6256
	ds_read_b128 v[40:43], v2 offset:6272
	ds_read_b128 v[48:51], v2 offset:6288
	ds_read_b128 v[52:55], v2 offset:6304
	ds_read_b128 v[60:63], v2 offset:6320
	s_waitcnt lgkmcnt(5)
	ds_read_b128 v[72:75], v2 offset:6336
	v_fma_f32 v3, -v195, v32, v217
	v_fma_f32 v27, -v15, v34, 0
	v_fma_f32 v32, -v13, v35, 0
	v_fma_f32 v3, -v11, v36, v3
	v_fma_f32 v25, -v9, v37, v25
	v_fma_f32 v27, -v7, v38, v27
	v_fma_f32 v32, -v4, v39, v32
	v_fma_f32 v3, -v5, v44, v3
	v_fma_f32 v25, -v6, v45, v25
	v_fma_f32 v27, -v8, v46, v27
	v_fma_f32 v32, -v10, v47, v32
	v_fma_f32 v3, -v12, v56, v3
	v_fma_f32 v25, -v14, v57, v25
	v_fma_f32 v27, -v16, v58, v27
	v_fma_f32 v32, -v18, v59, v32
	v_fma_f32 v3, -v19, v64, v3
	v_fma_f32 v25, -v20, v65, v25
	v_fma_f32 v27, -v21, v66, v27
	v_fma_f32 v32, -v22, v67, v32
	v_fma_f32 v3, -v23, v70, v3
	v_fma_f32 v25, -v71, v24, v25
	v_add_f32_e32 v3, v25, v3
	v_add_f32_e32 v25, v32, v27
	v_add_f32_e32 v25, v25, v3
	s_waitcnt lgkmcnt(5)
	v_fma_f32 v27, -v17, v29, 0
	ds_read_b128 v[32:35], v2 offset:6528
	ds_read_b128 v[36:39], v2 offset:6544
	ds_read_b128 v[44:47], v2 offset:6560
	ds_read_b128 v[56:59], v2 offset:6576
	ds_read_b128 v[64:67], v2 offset:6592
	ds_read_b128 v[68:71], v2 offset:6608
	v_fma_f32 v3, -v195, v28, v218
	v_fma_f32 v28, -v15, v30, 0
	v_fma_f32 v29, -v13, v31, 0
	s_waitcnt lgkmcnt(10)
	v_fma_f32 v3, -v11, v40, v3
	v_fma_f32 v27, -v9, v41, v27
	v_fma_f32 v28, -v7, v42, v28
	v_fma_f32 v29, -v4, v43, v29
	s_waitcnt lgkmcnt(9)
	v_fma_f32 v3, -v5, v48, v3
	v_fma_f32 v27, -v6, v49, v27
	v_fma_f32 v28, -v8, v50, v28
	v_fma_f32 v29, -v10, v51, v29
	s_waitcnt lgkmcnt(8)
	v_fma_f32 v3, -v12, v52, v3
	v_fma_f32 v27, -v14, v53, v27
	v_fma_f32 v28, -v16, v54, v28
	v_fma_f32 v29, -v18, v55, v29
	s_waitcnt lgkmcnt(7)
	v_fma_f32 v3, -v19, v60, v3
	v_fma_f32 v27, -v20, v61, v27
	v_fma_f32 v28, -v21, v62, v28
	v_fma_f32 v29, -v22, v63, v29
	s_waitcnt lgkmcnt(6)
	v_fma_f32 v3, -v23, v72, v3
	v_fma_f32 v27, -v24, v73, v27
	v_fma_f32 v28, -v74, v25, v28
	v_add_f32_e32 v3, v27, v3
	v_add_f32_e32 v27, v29, v28
	v_add_f32_e32 v27, v27, v3
	s_waitcnt lgkmcnt(5)
	v_fma_f32 v28, -v17, v33, 0
	ds_read_b128 v[40:43], v2 offset:6800
	ds_read_b128 v[48:51], v2 offset:6816
	ds_read_b128 v[52:55], v2 offset:6832
	ds_read_b128 v[60:63], v2 offset:6848
	ds_read_b128 v[72:75], v2 offset:6864
	ds_read_b128 v[76:79], v2 offset:6880
	ds_read_b128 v[140:143], v2 offset:6896
	v_fma_f32 v3, -v195, v32, v219
	v_fma_f32 v29, -v15, v34, 0
	v_fma_f32 v30, -v13, v35, 0
	s_waitcnt lgkmcnt(11)
	v_fma_f32 v3, -v11, v36, v3
	v_fma_f32 v28, -v9, v37, v28
	v_fma_f32 v29, -v7, v38, v29
	v_fma_f32 v30, -v4, v39, v30
	s_waitcnt lgkmcnt(10)
	v_fma_f32 v3, -v5, v44, v3
	v_fma_f32 v28, -v6, v45, v28
	v_fma_f32 v29, -v8, v46, v29
	v_fma_f32 v30, -v10, v47, v30
	s_waitcnt lgkmcnt(9)
	v_fma_f32 v3, -v12, v56, v3
	v_fma_f32 v28, -v14, v57, v28
	v_fma_f32 v29, -v16, v58, v29
	v_fma_f32 v30, -v18, v59, v30
	s_waitcnt lgkmcnt(8)
	v_fma_f32 v3, -v19, v64, v3
	v_fma_f32 v28, -v20, v65, v28
	v_fma_f32 v29, -v21, v66, v29
	v_fma_f32 v30, -v22, v67, v30
	s_waitcnt lgkmcnt(7)
	v_fma_f32 v3, -v23, v68, v3
	v_fma_f32 v28, -v24, v69, v28
	v_fma_f32 v29, -v25, v70, v29
	v_fma_f32 v30, -v71, v27, v30
	v_add_f32_e32 v3, v28, v3
	v_add_f32_e32 v28, v30, v29
	v_add_f32_e32 v28, v28, v3
	s_waitcnt lgkmcnt(6)
	v_fma_f32 v29, -v17, v41, 0
	ds_read_b128 v[30:33], v2 offset:7072
	ds_read_b128 v[34:37], v2 offset:7088
	ds_read_b128 v[44:47], v2 offset:7104
	ds_read_b128 v[56:59], v2 offset:7120
	ds_read_b128 v[64:67], v2 offset:7136
	ds_read_b128 v[68:71], v2 offset:7152
	s_waitcnt lgkmcnt(6)
	ds_read_b128 v[142:145], v2 offset:7168
	v_fma_f32 v3, -v195, v40, v220
	v_fma_f32 v38, -v15, v42, 0
	v_fma_f32 v39, -v13, v43, 0
	v_fma_f32 v3, -v11, v48, v3
	v_fma_f32 v29, -v9, v49, v29
	v_fma_f32 v38, -v7, v50, v38
	v_fma_f32 v39, -v4, v51, v39
	v_fma_f32 v3, -v5, v52, v3
	v_fma_f32 v29, -v6, v53, v29
	v_fma_f32 v38, -v8, v54, v38
	v_fma_f32 v39, -v10, v55, v39
	v_fma_f32 v3, -v12, v60, v3
	v_fma_f32 v29, -v14, v61, v29
	v_fma_f32 v38, -v16, v62, v38
	v_fma_f32 v39, -v18, v63, v39
	v_fma_f32 v3, -v19, v72, v3
	v_fma_f32 v29, -v20, v73, v29
	v_fma_f32 v38, -v21, v74, v38
	v_fma_f32 v39, -v22, v75, v39
	v_fma_f32 v3, -v23, v76, v3
	v_fma_f32 v29, -v24, v77, v29
	v_fma_f32 v38, -v25, v78, v38
	v_fma_f32 v39, -v27, v79, v39
	v_fma_f32 v3, -v140, v28, v3
	v_add_f32_e32 v3, v29, v3
	v_add_f32_e32 v29, v39, v38
	v_add_f32_e32 v29, v29, v3
	s_nop 0
	ds_read_b128 v[38:41], v2 offset:7344
	ds_read_b128 v[48:51], v2 offset:7360
	ds_read_b128 v[52:55], v2 offset:7376
	ds_read_b128 v[60:63], v2 offset:7392
	ds_read_b128 v[72:75], v2 offset:7408
	ds_read_b128 v[76:79], v2 offset:7424
	s_waitcnt lgkmcnt(6)
	ds_read_b128 v[144:147], v2 offset:7440
	v_fma_f32 v3, -v195, v30, v221
	v_fma_f32 v30, -v17, v31, 0
	v_fma_f32 v31, -v15, v32, 0
	v_fma_f32 v32, -v13, v33, 0
	v_fma_f32 v3, -v11, v34, v3
	v_fma_f32 v30, -v9, v35, v30
	v_fma_f32 v31, -v7, v36, v31
	v_fma_f32 v32, -v4, v37, v32
	v_fma_f32 v3, -v5, v44, v3
	v_fma_f32 v30, -v6, v45, v30
	v_fma_f32 v31, -v8, v46, v31
	v_fma_f32 v32, -v10, v47, v32
	v_fma_f32 v3, -v12, v56, v3
	v_fma_f32 v30, -v14, v57, v30
	v_fma_f32 v31, -v16, v58, v31
	v_fma_f32 v32, -v18, v59, v32
	v_fma_f32 v3, -v19, v64, v3
	v_fma_f32 v30, -v20, v65, v30
	v_fma_f32 v31, -v21, v66, v31
	v_fma_f32 v32, -v22, v67, v32
	v_fma_f32 v3, -v23, v68, v3
	v_fma_f32 v30, -v24, v69, v30
	v_fma_f32 v31, -v25, v70, v31
	v_fma_f32 v32, -v27, v71, v32
	v_fma_f32 v3, -v28, v142, v3
	v_fma_f32 v30, -v143, v29, v30
	v_add_f32_e32 v3, v30, v3
	v_add_f32_e32 v30, v32, v31
	v_add_f32_e32 v30, v30, v3
	s_waitcnt lgkmcnt(6)
	v_fma_f32 v31, -v17, v39, 0
	ds_read_b128 v[32:35], v2 offset:7616
	ds_read_b128 v[42:45], v2 offset:7632
	ds_read_b128 v[56:59], v2 offset:7648
	ds_read_b128 v[64:67], v2 offset:7664
	ds_read_b128 v[68:71], v2 offset:7680
	ds_read_b128 v[140:143], v2 offset:7696
	ds_read_b128 v[148:151], v2 offset:7712
	v_fma_f32 v3, -v195, v38, v222
	v_fma_f32 v36, -v15, v40, 0
	v_fma_f32 v37, -v13, v41, 0
	s_waitcnt lgkmcnt(12)
	v_fma_f32 v3, -v11, v48, v3
	v_fma_f32 v31, -v9, v49, v31
	v_fma_f32 v36, -v7, v50, v36
	v_fma_f32 v37, -v4, v51, v37
	s_waitcnt lgkmcnt(11)
	v_fma_f32 v3, -v5, v52, v3
	v_fma_f32 v31, -v6, v53, v31
	v_fma_f32 v36, -v8, v54, v36
	v_fma_f32 v37, -v10, v55, v37
	s_waitcnt lgkmcnt(10)
	v_fma_f32 v3, -v12, v60, v3
	v_fma_f32 v31, -v14, v61, v31
	v_fma_f32 v36, -v16, v62, v36
	v_fma_f32 v37, -v18, v63, v37
	s_waitcnt lgkmcnt(9)
	v_fma_f32 v3, -v19, v72, v3
	v_fma_f32 v31, -v20, v73, v31
	v_fma_f32 v36, -v21, v74, v36
	v_fma_f32 v37, -v22, v75, v37
	s_waitcnt lgkmcnt(8)
	v_fma_f32 v3, -v23, v76, v3
	v_fma_f32 v31, -v24, v77, v31
	v_fma_f32 v36, -v25, v78, v36
	v_fma_f32 v37, -v27, v79, v37
	s_waitcnt lgkmcnt(7)
	v_fma_f32 v3, -v28, v144, v3
	v_fma_f32 v31, -v29, v145, v31
	v_fma_f32 v36, -v146, v30, v36
	v_add_f32_e32 v3, v31, v3
	v_add_f32_e32 v31, v37, v36
	v_add_f32_e32 v31, v31, v3
	s_nop 0
	ds_read_b128 v[36:39], v2 offset:7888
	ds_read_b128 v[46:49], v2 offset:7904
	ds_read_b128 v[50:53], v2 offset:7920
	ds_read_b128 v[60:63], v2 offset:7936
	ds_read_b128 v[72:75], v2 offset:7952
	ds_read_b128 v[76:79], v2 offset:7968
	ds_read_b128 v[144:147], v2 offset:7984
	ds_read_b128 v[152:155], v2 offset:8000
	s_waitcnt lgkmcnt(14)
	v_fma_f32 v3, -v195, v32, v223
	v_fma_f32 v32, -v17, v33, 0
	v_fma_f32 v33, -v15, v34, 0
	v_fma_f32 v34, -v13, v35, 0
	s_waitcnt lgkmcnt(13)
	v_fma_f32 v3, -v11, v42, v3
	v_fma_f32 v32, -v9, v43, v32
	v_fma_f32 v33, -v7, v44, v33
	v_fma_f32 v34, -v4, v45, v34
	s_waitcnt lgkmcnt(12)
	v_fma_f32 v3, -v5, v56, v3
	v_fma_f32 v32, -v6, v57, v32
	v_fma_f32 v33, -v8, v58, v33
	v_fma_f32 v34, -v10, v59, v34
	s_waitcnt lgkmcnt(11)
	v_fma_f32 v3, -v12, v64, v3
	v_fma_f32 v32, -v14, v65, v32
	v_fma_f32 v33, -v16, v66, v33
	v_fma_f32 v34, -v18, v67, v34
	s_waitcnt lgkmcnt(10)
	v_fma_f32 v3, -v19, v68, v3
	v_fma_f32 v32, -v20, v69, v32
	v_fma_f32 v33, -v21, v70, v33
	v_fma_f32 v34, -v22, v71, v34
	s_waitcnt lgkmcnt(9)
	v_fma_f32 v3, -v23, v140, v3
	v_fma_f32 v32, -v24, v141, v32
	v_fma_f32 v33, -v25, v142, v33
	v_fma_f32 v34, -v27, v143, v34
	s_waitcnt lgkmcnt(8)
	v_fma_f32 v3, -v28, v148, v3
	v_fma_f32 v32, -v29, v149, v32
	v_fma_f32 v33, -v30, v150, v33
	v_fma_f32 v34, -v151, v31, v34
	v_add_f32_e32 v3, v32, v3
	v_add_f32_e32 v32, v34, v33
	v_add_f32_e32 v32, v32, v3
	s_waitcnt lgkmcnt(7)
	v_fma_f32 v33, -v17, v37, 0
	ds_read_b128 v[40:43], v2 offset:8160
	ds_read_b128 v[54:57], v2 offset:8176
	ds_read_b128 v[64:67], v2 offset:8192
	ds_read_b128 v[68:71], v2 offset:8208
	ds_read_b128 v[140:143], v2 offset:8224
	ds_read_b128 v[148:151], v2 offset:8240
	s_waitcnt lgkmcnt(6)
	ds_read_b128 v[154:157], v2 offset:8256
	ds_read_b128 v[158:161], v2 offset:8272
	v_fma_f32 v3, -v195, v36, v224
	v_fma_f32 v34, -v15, v38, 0
	v_fma_f32 v35, -v13, v39, 0
	v_fma_f32 v3, -v11, v46, v3
	v_fma_f32 v33, -v9, v47, v33
	v_fma_f32 v34, -v7, v48, v34
	v_fma_f32 v35, -v4, v49, v35
	v_fma_f32 v3, -v5, v50, v3
	v_fma_f32 v33, -v6, v51, v33
	v_fma_f32 v34, -v8, v52, v34
	v_fma_f32 v35, -v10, v53, v35
	v_fma_f32 v3, -v12, v60, v3
	v_fma_f32 v33, -v14, v61, v33
	v_fma_f32 v34, -v16, v62, v34
	v_fma_f32 v35, -v18, v63, v35
	v_fma_f32 v3, -v19, v72, v3
	v_fma_f32 v33, -v20, v73, v33
	v_fma_f32 v34, -v21, v74, v34
	v_fma_f32 v35, -v22, v75, v35
	v_fma_f32 v3, -v23, v76, v3
	v_fma_f32 v33, -v24, v77, v33
	v_fma_f32 v34, -v25, v78, v34
	v_fma_f32 v35, -v27, v79, v35
	v_fma_f32 v3, -v28, v144, v3
	v_fma_f32 v33, -v29, v145, v33
	v_fma_f32 v34, -v30, v146, v34
	v_fma_f32 v35, -v31, v147, v35
	v_fma_f32 v3, -v152, v32, v3
	v_add_f32_e32 v3, v33, v3
	v_add_f32_e32 v33, v35, v34
	v_add_f32_e32 v33, v33, v3
	s_waitcnt lgkmcnt(7)
	v_fma_f32 v34, -v17, v41, 0
	ds_read_b128 v[36:39], v2 offset:8432
	ds_read_b128 v[44:47], v2 offset:8448
	ds_read_b128 v[48:51], v2 offset:8464
	ds_read_b128 v[58:61], v2 offset:8480
	ds_read_b128 v[72:75], v2 offset:8496
	ds_read_b128 v[76:79], v2 offset:8512
	ds_read_b128 v[144:147], v2 offset:8528
	s_waitcnt lgkmcnt(7)
	ds_read_b128 v[160:163], v2 offset:8544
	v_fma_f32 v3, -v195, v40, v225
	v_fma_f32 v35, -v15, v42, 0
	v_fma_f32 v40, -v13, v43, 0
	v_fma_f32 v3, -v11, v54, v3
	v_fma_f32 v34, -v9, v55, v34
	v_fma_f32 v35, -v7, v56, v35
	v_fma_f32 v40, -v4, v57, v40
	v_fma_f32 v3, -v5, v64, v3
	v_fma_f32 v34, -v6, v65, v34
	v_fma_f32 v35, -v8, v66, v35
	v_fma_f32 v40, -v10, v67, v40
	v_fma_f32 v3, -v12, v68, v3
	v_fma_f32 v34, -v14, v69, v34
	v_fma_f32 v35, -v16, v70, v35
	v_fma_f32 v40, -v18, v71, v40
	v_fma_f32 v3, -v19, v140, v3
	v_fma_f32 v34, -v20, v141, v34
	v_fma_f32 v35, -v21, v142, v35
	v_fma_f32 v40, -v22, v143, v40
	v_fma_f32 v3, -v23, v148, v3
	v_fma_f32 v34, -v24, v149, v34
	v_fma_f32 v35, -v25, v150, v35
	v_fma_f32 v40, -v27, v151, v40
	v_fma_f32 v3, -v28, v154, v3
	v_fma_f32 v34, -v29, v155, v34
	v_fma_f32 v35, -v30, v156, v35
	v_fma_f32 v40, -v31, v157, v40
	v_fma_f32 v3, -v32, v158, v3
	v_fma_f32 v34, -v159, v33, v34
	v_add_f32_e32 v3, v34, v3
	v_add_f32_e32 v34, v40, v35
	v_add_f32_e32 v34, v34, v3
	s_waitcnt lgkmcnt(7)
	v_fma_f32 v3, -v17, v37, 0
	v_fma_f32 v2, -v195, v36, v226
	v_fma_f32 v35, -v15, v38, 0
	v_fma_f32 v36, -v13, v39, 0
	s_waitcnt lgkmcnt(6)
	v_fma_f32 v2, -v11, v44, v2
	v_fma_f32 v3, -v9, v45, v3
	v_fma_f32 v35, -v7, v46, v35
	v_fma_f32 v36, -v4, v47, v36
	s_waitcnt lgkmcnt(5)
	v_fma_f32 v2, -v5, v48, v2
	v_fma_f32 v3, -v6, v49, v3
	v_fma_f32 v35, -v8, v50, v35
	v_fma_f32 v36, -v10, v51, v36
	s_waitcnt lgkmcnt(4)
	v_fma_f32 v2, -v12, v58, v2
	v_fma_f32 v3, -v14, v59, v3
	v_fma_f32 v35, -v16, v60, v35
	v_fma_f32 v36, -v18, v61, v36
	s_waitcnt lgkmcnt(3)
	v_fma_f32 v2, -v19, v72, v2
	v_fma_f32 v3, -v20, v73, v3
	v_fma_f32 v35, -v21, v74, v35
	v_fma_f32 v36, -v22, v75, v36
	s_waitcnt lgkmcnt(2)
	v_fma_f32 v2, -v23, v76, v2
	v_fma_f32 v3, -v24, v77, v3
	v_fma_f32 v35, -v25, v78, v35
	v_fma_f32 v36, -v27, v79, v36
	s_waitcnt lgkmcnt(1)
	v_fma_f32 v2, -v28, v144, v2
	v_fma_f32 v3, -v29, v145, v3
	v_fma_f32 v35, -v30, v146, v35
	v_fma_f32 v36, -v31, v147, v36
	s_waitcnt lgkmcnt(0)
	v_fma_f32 v2, -v32, v160, v2
	v_fma_f32 v3, -v33, v161, v3
	v_fma_f32 v35, -v162, v34, v35
	v_add_f32_e32 v2, v3, v2
	v_add_f32_e32 v3, v36, v35
	v_add_f32_e32 v35, v3, v2
	ds_read2st64_b32 v[2:3], v186 offset1:2
	s_waitcnt lgkmcnt(0)
	v_mul_f32_e32 v36, v2, v3
	v_mul_f32_e32 v3, v195, v2
	v_cvt_pk_bf16_f32 v3, v3, v3
	ds_write_b16 v190, v3
	v_mul_f32_e32 v3, v195, v36
	v_cvt_pk_bf16_f32 v3, v3, v3
	ds_write_b16 v190, v3 offset:64
	v_add_u32_e32 v3, v171, v189
	s_and_saveexec_b64 s[18:19], s[8:9]
	ds_write_b16 v3, v227 offset:128
	s_or_b64 exec, exec, s[18:19]
	v_mul_f32_e32 v37, v17, v2
	v_cvt_pk_bf16_f32 v37, v37, v37
	ds_write_b16 v190, v37 offset:272
	v_mul_f32_e32 v37, v17, v36
	v_cvt_pk_bf16_f32 v37, v37, v37
	ds_write_b16 v190, v37 offset:336
	s_and_saveexec_b64 s[18:19], s[8:9]
	v_cvt_pk_bf16_f32 v17, -v17, -v17
	ds_write_b16 v3, v17 offset:400
	s_or_b64 exec, exec, s[18:19]
	v_mul_f32_e32 v17, v15, v2
	v_cvt_pk_bf16_f32 v17, v17, v17
	ds_write_b16 v190, v17 offset:544
	v_mul_f32_e32 v17, v15, v36
	v_cvt_pk_bf16_f32 v17, v17, v17
	ds_write_b16 v190, v17 offset:608
	s_and_saveexec_b64 s[18:19], s[8:9]
	v_cvt_pk_bf16_f32 v15, -v15, -v15
	ds_write_b16 v3, v15 offset:672
	s_or_b64 exec, exec, s[18:19]
	v_mul_f32_e32 v15, v13, v2
	v_cvt_pk_bf16_f32 v15, v15, v15
	ds_write_b16 v190, v15 offset:816
	v_mul_f32_e32 v15, v13, v36
	v_cvt_pk_bf16_f32 v15, v15, v15
	ds_write_b16 v190, v15 offset:880
	s_and_saveexec_b64 s[18:19], s[8:9]
	v_cvt_pk_bf16_f32 v13, -v13, -v13
	ds_write_b16 v3, v13 offset:944
	s_or_b64 exec, exec, s[18:19]
	v_mul_f32_e32 v13, v11, v2
	v_cvt_pk_bf16_f32 v13, v13, v13
	ds_write_b16 v190, v13 offset:1088
	v_mul_f32_e32 v13, v11, v36
	v_cvt_pk_bf16_f32 v13, v13, v13
	ds_write_b16 v190, v13 offset:1152
	s_and_saveexec_b64 s[18:19], s[8:9]
	v_cvt_pk_bf16_f32 v11, -v11, -v11
	ds_write_b16 v3, v11 offset:1216
	s_or_b64 exec, exec, s[18:19]
	v_mul_f32_e32 v11, v9, v2
	v_cvt_pk_bf16_f32 v11, v11, v11
	ds_write_b16 v190, v11 offset:1360
	v_mul_f32_e32 v11, v9, v36
	v_cvt_pk_bf16_f32 v11, v11, v11
	ds_write_b16 v190, v11 offset:1424
	s_and_saveexec_b64 s[18:19], s[8:9]
	v_cvt_pk_bf16_f32 v9, -v9, -v9
	ds_write_b16 v3, v9 offset:1488
	s_or_b64 exec, exec, s[18:19]
	v_mul_f32_e32 v9, v7, v2
	v_cvt_pk_bf16_f32 v9, v9, v9
	ds_write_b16 v190, v9 offset:1632
	v_mul_f32_e32 v9, v7, v36
	v_cvt_pk_bf16_f32 v9, v9, v9
	ds_write_b16 v190, v9 offset:1696
	s_and_saveexec_b64 s[18:19], s[8:9]
	v_cvt_pk_bf16_f32 v7, -v7, -v7
	ds_write_b16 v3, v7 offset:1760
	s_or_b64 exec, exec, s[18:19]
	v_mul_f32_e32 v7, v4, v2
	v_cvt_pk_bf16_f32 v7, v7, v7
	ds_write_b16 v190, v7 offset:1904
	v_mul_f32_e32 v7, v4, v36
	v_cvt_pk_bf16_f32 v7, v7, v7
	ds_write_b16 v190, v7 offset:1968
	s_and_saveexec_b64 s[18:19], s[8:9]
	v_cvt_pk_bf16_f32 v4, -v4, -v4
	ds_write_b16 v3, v4 offset:2032
	s_or_b64 exec, exec, s[18:19]
	v_mul_f32_e32 v4, v5, v2
	v_cvt_pk_bf16_f32 v4, v4, v4
	ds_write_b16 v190, v4 offset:2176
	v_mul_f32_e32 v4, v5, v36
	v_cvt_pk_bf16_f32 v4, v4, v4
	ds_write_b16 v190, v4 offset:2240
	s_and_saveexec_b64 s[18:19], s[8:9]
	v_cvt_pk_bf16_f32 v4, -v5, -v5
	ds_write_b16 v3, v4 offset:2304
	s_or_b64 exec, exec, s[18:19]
	v_mul_f32_e32 v4, v6, v2
	v_cvt_pk_bf16_f32 v4, v4, v4
	ds_write_b16 v190, v4 offset:2448
	v_mul_f32_e32 v4, v6, v36
	v_cvt_pk_bf16_f32 v4, v4, v4
	ds_write_b16 v190, v4 offset:2512
	s_and_saveexec_b64 s[18:19], s[8:9]
	v_cvt_pk_bf16_f32 v4, -v6, -v6
	ds_write_b16 v3, v4 offset:2576
	s_or_b64 exec, exec, s[18:19]
	v_mul_f32_e32 v4, v8, v2
	v_cvt_pk_bf16_f32 v4, v4, v4
	ds_write_b16 v190, v4 offset:2720
	v_mul_f32_e32 v4, v8, v36
	v_cvt_pk_bf16_f32 v4, v4, v4
	ds_write_b16 v190, v4 offset:2784
	s_and_saveexec_b64 s[18:19], s[8:9]
	v_cvt_pk_bf16_f32 v4, -v8, -v8
	ds_write_b16 v3, v4 offset:2848
	s_or_b64 exec, exec, s[18:19]
	v_mul_f32_e32 v4, v10, v2
	v_cvt_pk_bf16_f32 v4, v4, v4
	ds_write_b16 v190, v4 offset:2992
	v_mul_f32_e32 v4, v10, v36
	v_cvt_pk_bf16_f32 v4, v4, v4
	ds_write_b16 v190, v4 offset:3056
	s_and_saveexec_b64 s[18:19], s[8:9]
	v_cvt_pk_bf16_f32 v4, -v10, -v10
	ds_write_b16 v3, v4 offset:3120
	s_or_b64 exec, exec, s[18:19]
	v_mul_f32_e32 v4, v12, v2
	v_cvt_pk_bf16_f32 v4, v4, v4
	ds_write_b16 v190, v4 offset:3264
	v_mul_f32_e32 v4, v12, v36
	v_cvt_pk_bf16_f32 v4, v4, v4
	ds_write_b16 v190, v4 offset:3328
	s_and_saveexec_b64 s[18:19], s[8:9]
	v_cvt_pk_bf16_f32 v4, -v12, -v12
	ds_write_b16 v3, v4 offset:3392
	s_or_b64 exec, exec, s[18:19]
	v_mul_f32_e32 v4, v14, v2
	v_cvt_pk_bf16_f32 v4, v4, v4
	ds_write_b16 v190, v4 offset:3536
	v_mul_f32_e32 v4, v14, v36
	v_cvt_pk_bf16_f32 v4, v4, v4
	ds_write_b16 v190, v4 offset:3600
	s_and_saveexec_b64 s[18:19], s[8:9]
	v_cvt_pk_bf16_f32 v4, -v14, -v14
	ds_write_b16 v3, v4 offset:3664
	s_or_b64 exec, exec, s[18:19]
	v_mul_f32_e32 v4, v16, v2
	v_cvt_pk_bf16_f32 v4, v4, v4
	ds_write_b16 v190, v4 offset:3808
	v_mul_f32_e32 v4, v16, v36
	v_cvt_pk_bf16_f32 v4, v4, v4
	ds_write_b16 v190, v4 offset:3872
	s_and_saveexec_b64 s[18:19], s[8:9]
	v_cvt_pk_bf16_f32 v4, -v16, -v16
	ds_write_b16 v3, v4 offset:3936
	s_or_b64 exec, exec, s[18:19]
	v_mul_f32_e32 v4, v18, v2
	v_cvt_pk_bf16_f32 v4, v4, v4
	ds_write_b16 v190, v4 offset:4080
	v_mul_f32_e32 v4, v18, v36
	v_cvt_pk_bf16_f32 v4, v4, v4
	ds_write_b16 v190, v4 offset:4144
	s_and_saveexec_b64 s[18:19], s[8:9]
	v_cvt_pk_bf16_f32 v4, -v18, -v18
	ds_write_b16 v3, v4 offset:4208
	s_or_b64 exec, exec, s[18:19]
	v_mul_f32_e32 v4, v19, v2
	v_cvt_pk_bf16_f32 v4, v4, v4
	ds_write_b16 v190, v4 offset:4352
	v_mul_f32_e32 v4, v19, v36
	v_cvt_pk_bf16_f32 v4, v4, v4
	ds_write_b16 v190, v4 offset:4416
	s_and_saveexec_b64 s[18:19], s[8:9]
	v_cvt_pk_bf16_f32 v4, -v19, -v19
	ds_write_b16 v3, v4 offset:4480
	s_or_b64 exec, exec, s[18:19]
	v_mul_f32_e32 v4, v20, v2
	v_cvt_pk_bf16_f32 v4, v4, v4
	ds_write_b16 v190, v4 offset:4624
	v_mul_f32_e32 v4, v20, v36
	v_cvt_pk_bf16_f32 v4, v4, v4
	ds_write_b16 v190, v4 offset:4688
	s_and_saveexec_b64 s[18:19], s[8:9]
	v_cvt_pk_bf16_f32 v4, -v20, -v20
	ds_write_b16 v3, v4 offset:4752
	s_or_b64 exec, exec, s[18:19]
	v_mul_f32_e32 v4, v21, v2
	v_cvt_pk_bf16_f32 v4, v4, v4
	ds_write_b16 v190, v4 offset:4896
	v_mul_f32_e32 v4, v21, v36
	v_cvt_pk_bf16_f32 v4, v4, v4
	ds_write_b16 v190, v4 offset:4960
	s_and_saveexec_b64 s[18:19], s[8:9]
	v_cvt_pk_bf16_f32 v4, -v21, -v21
	ds_write_b16 v3, v4 offset:5024
	s_or_b64 exec, exec, s[18:19]
	v_mul_f32_e32 v4, v22, v2
	v_cvt_pk_bf16_f32 v4, v4, v4
	ds_write_b16 v190, v4 offset:5168
	v_mul_f32_e32 v4, v22, v36
	v_cvt_pk_bf16_f32 v4, v4, v4
	ds_write_b16 v190, v4 offset:5232
	s_and_saveexec_b64 s[18:19], s[8:9]
	v_cvt_pk_bf16_f32 v4, -v22, -v22
	ds_write_b16 v3, v4 offset:5296
	s_or_b64 exec, exec, s[18:19]
	v_mul_f32_e32 v4, v23, v2
	v_cvt_pk_bf16_f32 v4, v4, v4
	ds_write_b16 v190, v4 offset:5440
	v_mul_f32_e32 v4, v23, v36
	v_cvt_pk_bf16_f32 v4, v4, v4
	ds_write_b16 v190, v4 offset:5504
	s_and_saveexec_b64 s[18:19], s[8:9]
	v_cvt_pk_bf16_f32 v4, -v23, -v23
	ds_write_b16 v3, v4 offset:5568
	s_or_b64 exec, exec, s[18:19]
	v_mul_f32_e32 v4, v24, v2
	v_cvt_pk_bf16_f32 v4, v4, v4
	ds_write_b16 v190, v4 offset:5712
	v_mul_f32_e32 v4, v24, v36
	v_cvt_pk_bf16_f32 v4, v4, v4
	ds_write_b16 v190, v4 offset:5776
	s_and_saveexec_b64 s[18:19], s[8:9]
	v_cvt_pk_bf16_f32 v4, -v24, -v24
	ds_write_b16 v3, v4 offset:5840
	s_or_b64 exec, exec, s[18:19]
	v_mul_f32_e32 v4, v25, v2
	v_cvt_pk_bf16_f32 v4, v4, v4
	ds_write_b16 v190, v4 offset:5984
	v_mul_f32_e32 v4, v25, v36
	v_cvt_pk_bf16_f32 v4, v4, v4
	ds_write_b16 v190, v4 offset:6048
	s_and_saveexec_b64 s[18:19], s[8:9]
	v_cvt_pk_bf16_f32 v4, -v25, -v25
	ds_write_b16 v3, v4 offset:6112
	s_or_b64 exec, exec, s[18:19]
	v_mul_f32_e32 v4, v27, v2
	v_cvt_pk_bf16_f32 v4, v4, v4
	ds_write_b16 v190, v4 offset:6256
	v_mul_f32_e32 v4, v27, v36
	v_cvt_pk_bf16_f32 v4, v4, v4
	ds_write_b16 v190, v4 offset:6320
	s_and_saveexec_b64 s[18:19], s[8:9]
	v_cvt_pk_bf16_f32 v4, -v27, -v27
	ds_write_b16 v3, v4 offset:6384
	s_or_b64 exec, exec, s[18:19]
	v_mul_f32_e32 v4, v28, v2
	v_cvt_pk_bf16_f32 v4, v4, v4
	ds_write_b16 v190, v4 offset:6528
	v_mul_f32_e32 v4, v28, v36
	v_cvt_pk_bf16_f32 v4, v4, v4
	ds_write_b16 v190, v4 offset:6592
	s_and_saveexec_b64 s[18:19], s[8:9]
	v_cvt_pk_bf16_f32 v4, -v28, -v28
	ds_write_b16 v3, v4 offset:6656
	s_or_b64 exec, exec, s[18:19]
	v_mul_f32_e32 v4, v29, v2
	v_cvt_pk_bf16_f32 v4, v4, v4
	ds_write_b16 v190, v4 offset:6800
	v_mul_f32_e32 v4, v29, v36
	v_cvt_pk_bf16_f32 v4, v4, v4
	ds_write_b16 v190, v4 offset:6864
	s_and_saveexec_b64 s[18:19], s[8:9]
	v_cvt_pk_bf16_f32 v4, -v29, -v29
	ds_write_b16 v3, v4 offset:6928
	s_or_b64 exec, exec, s[18:19]
	v_mul_f32_e32 v4, v30, v2
	v_cvt_pk_bf16_f32 v4, v4, v4
	ds_write_b16 v190, v4 offset:7072
	v_mul_f32_e32 v4, v30, v36
	v_cvt_pk_bf16_f32 v4, v4, v4
	ds_write_b16 v190, v4 offset:7136
	s_and_saveexec_b64 s[18:19], s[8:9]
	v_cvt_pk_bf16_f32 v4, -v30, -v30
	ds_write_b16 v3, v4 offset:7200
	s_or_b64 exec, exec, s[18:19]
	v_mul_f32_e32 v4, v31, v2
	v_cvt_pk_bf16_f32 v4, v4, v4
	ds_write_b16 v190, v4 offset:7344
	v_mul_f32_e32 v4, v31, v36
	v_cvt_pk_bf16_f32 v4, v4, v4
	ds_write_b16 v190, v4 offset:7408
	s_and_saveexec_b64 s[18:19], s[8:9]
	v_cvt_pk_bf16_f32 v4, -v31, -v31
	ds_write_b16 v3, v4 offset:7472
	s_or_b64 exec, exec, s[18:19]
	v_mul_f32_e32 v4, v32, v2
	v_cvt_pk_bf16_f32 v4, v4, v4
	ds_write_b16 v190, v4 offset:7616
	v_mul_f32_e32 v4, v32, v36
	v_cvt_pk_bf16_f32 v4, v4, v4
	ds_write_b16 v190, v4 offset:7680
	s_and_saveexec_b64 s[18:19], s[8:9]
	v_cvt_pk_bf16_f32 v4, -v32, -v32
	ds_write_b16 v3, v4 offset:7744
	s_or_b64 exec, exec, s[18:19]
	v_mul_f32_e32 v4, v33, v2
	v_cvt_pk_bf16_f32 v4, v4, v4
	ds_write_b16 v190, v4 offset:7888
	v_mul_f32_e32 v4, v33, v36
	v_cvt_pk_bf16_f32 v4, v4, v4
	ds_write_b16 v190, v4 offset:7952
	s_and_saveexec_b64 s[18:19], s[8:9]
	v_cvt_pk_bf16_f32 v4, -v33, -v33
	ds_write_b16 v3, v4 offset:8016
	s_or_b64 exec, exec, s[18:19]
	v_mul_f32_e32 v4, v34, v2
	v_cvt_pk_bf16_f32 v4, v4, v4
	ds_write_b16 v190, v4 offset:8160
	v_mul_f32_e32 v4, v34, v36
	v_cvt_pk_bf16_f32 v4, v4, v4
	ds_write_b16 v190, v4 offset:8224
	s_and_saveexec_b64 s[18:19], s[8:9]
	v_cvt_pk_bf16_f32 v4, -v34, -v34
	ds_write_b16 v3, v4 offset:8288
	s_or_b64 exec, exec, s[18:19]
	v_mul_f32_e32 v2, v35, v2
	v_cvt_pk_bf16_f32 v2, v2, v2
	ds_write_b16 v190, v2 offset:8432
	v_mul_f32_e32 v2, v35, v36
	v_cvt_pk_bf16_f32 v2, v2, v2
	ds_write_b16 v190, v2 offset:8496
	s_and_saveexec_b64 s[18:19], s[8:9]
	v_cvt_pk_bf16_f32 v2, -v35, -v35
	ds_write_b16 v3, v2 offset:8560
	s_or_b64 exec, exec, s[18:19]
